# v9 plus four p1 exp2 ops moved from the second QK MFMA gap into the K-fragment read shadow
# baseline (speedup 1.0000x reference)
; #define SBAR() __builtin_amdgcn_sched_barrier(0)
; #define DMA(slot, t) do { \
;     __builtin_amdgcn_global_load_lds((const unsigned*)(Kg + (long)(t) * (64 * 256)), (LAS unsigned*)(L3 + K_OFF + (slot) * SHM_T + wid * 1024), 16, 0, 0); \
;     __builtin_amdgcn_global_load_lds((const unsigned*)(Vg + (long)(t) * 8192), (LAS unsigned*)(L3 + (slot) * SHM_T + wid * 1024), 16, 0, 0); } while (0)
; #define QKT(P0, P1, b) qkt(P0, P1, nm, K_lds + (b) * SHM_T, qr, ko, c00, c01, c10, c11)
; #define PIPE1() do { SGB(0x100, 8); SGB(0x400, 4); SGB(0x008, 1); SGB(0x400, 4); SGB(0x008, 1); SGB(0x400, 4); SGB(0x008, 1); SGB(0x400, 4); SGB(0x008, 1); } while (0)
; #define HALF2(Y0, Y1, alY, b) do { PVL(b); const float pm_ = max32(Y0, Y1); adjustSM(Y0, Y1, nm, alY, pm_); SBAR(); \
;     PVM(); exp16(Y0); asm volatile("" : "+v"(Y0)); \
;     SGB(0x008, 1); SGB(0x400, 3); SGB(0x008, 1); SGB(0x400, 3); SGB(0x008, 1); SGB(0x400, 3); SGB(0x008, 1); SGB(0x400, 3); SGB(0x008, 1); SGB(0x400, 4); SBAR(); } while (0)
; __device__ __forceinline__ void finishSM(f32x16& p0, f32x16& p1, v8i& pf) {
;   for (int r = 0; r < 16; ++r) p1[r] = __builtin_amdgcn_exp2f(p1[r]);
; #pragma unroll
;   for (int j = 0; j < 4; ++j) {
;     int a = __builtin_amdgcn_cvt_pk_fp8_f32(p0[4 * j], p0[4 * j + 1], 0, false); a = __builtin_amdgcn_cvt_pk_fp8_f32(p0[4 * j + 2], p0[4 * j + 3], a, true);
;     int b = __builtin_amdgcn_cvt_pk_fp8_f32(p1[4 * j], p1[4 * j + 1], 0, false); b = __builtin_amdgcn_cvt_pk_fp8_f32(p1[4 * j + 2], p1[4 * j + 3], b, true);
;     auto rr = __builtin_amdgcn_permlane32_swap((unsigned)a, (unsigned)b, false, false);
;     pf[2 * j] = (int)rr[0]; pf[2 * j + 1] = (int)rr[1]; }
; }
; __device__ __forceinline__ void body(const unsigned char* Q8b, const unsigned char* K8h, const unsigned char* VT8h, const bf16_t* Gb, bf16_t* Ob, int seq, char* lds, const int wid, ...
;     ...
;   for (int i = 0; i + 2 < NT; i += 2) {
;     SBAR(); QKT(pB0, pB1, (s0 + 1) & 3);
;     finishSM(pA0, pA1, pf); PIPE1(); SBAR();
;     DMA((s0 + 3) & 3, i + 3);
;     SBAR();
;     HALF2(pB0, pB1, alB, s0);
.LBB0_374:
	ds_read_b128 v[2:5], v242 offset:40960
	ds_read_b128 v[6:9], v243 offset:40960
	ds_read_b128 v[128:131], v242 offset:45056
	ds_read_b128 v[132:135], v243 offset:45056
	ds_read_b128 v[194:197], v244 offset:40960
	ds_read_b128 v[198:201], v245 offset:40960
	ds_read_b128 v[246:249], v244 offset:45056
	ds_read_b128 v[250:253], v245 offset:45056
	v_exp_f32_e32 v1, v112
	v_exp_f32_e32 v10, v113
	v_exp_f32_e32 v11, v114
	v_exp_f32_e32 v12, v115
	v_exp_f32_e32 v13, v120
	v_exp_f32_e32 v14, v121
	v_exp_f32_e32 v15, v122
	v_exp_f32_e32 v112, v123
	s_waitcnt lgkmcnt(6)
	s_setprio 1
	v_mfma_scale_f32_32x32x64_f8f6f4 v[160:175], v[2:9], v[176:183], v[96:111], v240, v239 op_sel_hi:[0,0,0]
	v_exp_f32_e32 v6, v116
	v_exp_f32_e32 v7, v117
	v_exp_f32_e32 v8, v118
	v_exp_f32_e32 v9, v119
	v_cvt_pk_fp8_f32 v5, v6, v7
	v_cvt_pk_fp8_f32 v3, v1, v10
	v_cvt_pk_fp8_f32 v5, v8, v9 op_sel:[0,0,1]
	s_waitcnt lgkmcnt(4)
	v_mfma_scale_f32_32x32x64_f8f6f4 v[128:143], v[128:135], v[176:183], v[96:111], v240, v239 op_sel_hi:[0,0,0]
	v_cvt_pk_fp8_f32 v2, v144, v145
	v_cvt_pk_fp8_f32 v4, v148, v149
	v_cvt_pk_fp8_f32 v6, v152, v153
	v_cvt_pk_fp8_f32 v7, v13, v14
	v_cvt_pk_fp8_f32 v8, v156, v157
	v_cvt_pk_fp8_f32 v2, v146, v147 op_sel:[0,0,1]
	v_cvt_pk_fp8_f32 v3, v11, v12 op_sel:[0,0,1]
	v_cvt_pk_fp8_f32 v4, v150, v151 op_sel:[0,0,1]
	v_cvt_pk_fp8_f32 v6, v154, v155 op_sel:[0,0,1]
	v_cvt_pk_fp8_f32 v7, v15, v112 op_sel:[0,0,1]
	v_cvt_pk_fp8_f32 v8, v158, v159 op_sel:[0,0,1]
	s_waitcnt lgkmcnt(2)
	v_mfma_scale_f32_32x32x64_f8f6f4 v[160:175], v[194:201], v[184:191], v[160:175], v240, v239 op_sel_hi:[0,0,0]
	v_exp_f32_e32 v113, v124
	v_exp_f32_e32 v114, v125
	v_exp_f32_e32 v1, v126
	v_exp_f32_e32 v10, v127
	v_permlane32_swap_b32_e32 v2, v3
	v_cvt_pk_fp8_f32 v9, v113, v114
	v_permlane32_swap_b32_e32 v4, v5
	v_permlane32_swap_b32_e32 v6, v7
	v_cvt_pk_fp8_f32 v9, v1, v10 op_sel:[0,0,1]
	s_nop 1
	v_permlane32_swap_b32_e32 v8, v9
	s_waitcnt lgkmcnt(0)
	v_mfma_scale_f32_32x32x64_f8f6f4 v[128:143], v[246:253], v[184:191], v[128:143], v240, v239 op_sel_hi:[0,0,0]
	s_setprio 0
	s_add_i32 m0, s68, 0xe000
	s_nop 0
	global_load_lds_dwordx4 v192, s[98:99]
	s_add_i32 m0, s68, 0x6000
	s_nop 0
	global_load_lds_dwordx4 v193, s[100:101]
	ds_read_b128 v[194:197], v254
	ds_read_b128 v[148:151], v254 offset:2048
	ds_read_b128 v[198:201], v255
	ds_read_b128 v[152:155], v255 offset:2048
	ds_read_b128 v[120:123], v254 offset:4096
	ds_read_b128 v[112:115], v254 offset:6144
	ds_read_b128 v[124:127], v255 offset:4096
	ds_read_b128 v[116:119], v255 offset:6144
	v_max_f32_e32 v1, v160, v161
	v_max3_f32 v1, v1, v162, v163
	v_max3_f32 v1, v1, v164, v165
	v_max3_f32 v1, v1, v166, v167
	v_max3_f32 v1, v1, v168, v169
	v_max3_f32 v1, v1, v170, v171
	v_max3_f32 v1, v1, v172, v173
	v_max3_f32 v1, v1, v174, v175
	v_max3_f32 v1, v1, v128, v129
	v_max3_f32 v1, v1, v130, v131
	v_max3_f32 v1, v1, v132, v133
	v_max3_f32 v1, v1, v134, v135
	v_max3_f32 v1, v1, v136, v137
	v_max3_f32 v1, v1, v138, v139
	v_max3_f32 v1, v1, v140, v141
	v_max3_f32 v1, v1, v142, v143
	v_cmp_lt_f32_e32 vcc, s80, v1
	s_cbranch_vccnz .LBB0_383

; #define SBAR() __builtin_amdgcn_sched_barrier(0)
; #define QKT(P0, P1, b) qkt(P0, P1, nm, K_lds + (b) * SHM_T, qr, ko, c00, c01, c10, c11)
; #define PIPE1() do { SGB(0x100, 8); SGB(0x400, 4); SGB(0x008, 1); SGB(0x400, 4); SGB(0x008, 1); SGB(0x400, 4); SGB(0x008, 1); SGB(0x400, 4); SGB(0x008, 1); } while (0)
; __device__ __forceinline__ void finishSM(f32x16& p0, f32x16& p1, v8i& pf) {
;   for (int r = 0; r < 16; ++r) p1[r] = __builtin_amdgcn_exp2f(p1[r]);
; #pragma unroll
;   for (int j = 0; j < 4; ++j) {
;     int a = __builtin_amdgcn_cvt_pk_fp8_f32(p0[4 * j], p0[4 * j + 1], 0, false); a = __builtin_amdgcn_cvt_pk_fp8_f32(p0[4 * j + 2], p0[4 * j + 3], a, true);
;     int b = __builtin_amdgcn_cvt_pk_fp8_f32(p1[4 * j], p1[4 * j + 1], 0, false); b = __builtin_amdgcn_cvt_pk_fp8_f32(p1[4 * j + 2], p1[4 * j + 3], b, true);
;     auto rr = __builtin_amdgcn_permlane32_swap((unsigned)a, (unsigned)b, false, false);
;     pf[2 * j] = (int)rr[0]; pf[2 * j + 1] = (int)rr[1]; }
; }
; __device__ __forceinline__ void body(const unsigned char* Q8b, const unsigned char* K8h, const unsigned char* VT8h, const bf16_t* Gb, bf16_t* Ob, int seq, char* lds, const int wid, ...
;     ...
;     SBAR(); QKT(pA0, pA1, (s0 + 2) & 3);
;     finishSM(pB0, pB1, pf); PIPE1(); SBAR();
.Lstg_a1:
	ds_read_b128 v[2:5], v242 offset:49152
	ds_read_b128 v[6:9], v243 offset:49152
	ds_read_b128 v[112:115], v242 offset:53248
	ds_read_b128 v[116:119], v243 offset:53248
	ds_read_b128 v[194:197], v244 offset:49152
	ds_read_b128 v[198:201], v245 offset:49152
	ds_read_b128 v[246:249], v244 offset:53248
	ds_read_b128 v[250:253], v245 offset:53248
	v_exp_f32_e32 v1, v128
	v_exp_f32_e32 v10, v129
	v_exp_f32_e32 v11, v130
	v_exp_f32_e32 v12, v131
	v_exp_f32_e32 v13, v136
	v_exp_f32_e32 v14, v137
	v_exp_f32_e32 v15, v138
	v_exp_f32_e32 v128, v139
	s_waitcnt lgkmcnt(6)
	s_setprio 1
	v_mfma_scale_f32_32x32x64_f8f6f4 v[160:175], v[2:9], v[176:183], v[96:111], v240, v239 op_sel_hi:[0,0,0]
	v_exp_f32_e32 v6, v132
	v_exp_f32_e32 v7, v133
	v_exp_f32_e32 v8, v134
	v_exp_f32_e32 v9, v135
	v_cvt_pk_fp8_f32 v5, v6, v7
	v_cvt_pk_fp8_f32 v2, v144, v145
	v_cvt_pk_fp8_f32 v5, v8, v9 op_sel:[0,0,1]
	s_waitcnt lgkmcnt(4)
	v_mfma_scale_f32_32x32x64_f8f6f4 v[112:127], v[112:119], v[176:183], v[96:111], v240, v239 op_sel_hi:[0,0,0]
	v_cvt_pk_fp8_f32 v3, v1, v10
	v_cvt_pk_fp8_f32 v4, v148, v149
	v_cvt_pk_fp8_f32 v6, v152, v153
	v_cvt_pk_fp8_f32 v7, v13, v14
	v_cvt_pk_fp8_f32 v8, v156, v157
	v_cvt_pk_fp8_f32 v2, v146, v147 op_sel:[0,0,1]
	v_cvt_pk_fp8_f32 v3, v11, v12 op_sel:[0,0,1]
	v_cvt_pk_fp8_f32 v4, v150, v151 op_sel:[0,0,1]
	v_cvt_pk_fp8_f32 v6, v154, v155 op_sel:[0,0,1]
	v_cvt_pk_fp8_f32 v7, v15, v128 op_sel:[0,0,1]
	v_cvt_pk_fp8_f32 v8, v158, v159 op_sel:[0,0,1]
	s_waitcnt lgkmcnt(2)
	v_mfma_scale_f32_32x32x64_f8f6f4 v[160:175], v[194:201], v[184:191], v[160:175], v240, v239 op_sel_hi:[0,0,0]
	v_exp_f32_e32 v129, v140
	v_exp_f32_e32 v130, v141
	v_exp_f32_e32 v131, v142
	v_exp_f32_e32 v132, v143
	v_permlane32_swap_b32_e32 v2, v3
	v_cvt_pk_fp8_f32 v9, v129, v130
	v_permlane32_swap_b32_e32 v4, v5
	v_permlane32_swap_b32_e32 v6, v7
	v_cvt_pk_fp8_f32 v9, v131, v132 op_sel:[0,0,1]
	s_nop 1
	v_permlane32_swap_b32_e32 v8, v9
	s_waitcnt lgkmcnt(0)
	v_mfma_scale_f32_32x32x64_f8f6f4 v[112:127], v[246:253], v[184:191], v[112:127], v240, v239 op_sel_hi:[0,0,0]
	s_setprio 0
	s_min_u32 s36, s45, 0x7b
	s_add_i32 s56, s36, 4
	s_lshl_b32 s36, s56, 14
	s_add_i32 s57, s68, 0x0
	s_add_u32 s88, s94, s36
	s_addc_u32 s89, s95, 0
	s_add_i32 m0, s57, 0x8000
	s_lshl_b32 s36, s56, 13
	s_add_u32 s90, s96, s36
	s_addc_u32 s91, s97, 0
	global_load_lds_dwordx4 v192, s[88:89]
	s_mov_b32 m0, s57
	s_nop 0
	global_load_lds_dwordx4 v193, s[90:91]
	ds_read_b128 v[194:197], v254 offset:8192
	ds_read_b128 v[148:151], v254 offset:10240
	ds_read_b128 v[198:201], v255 offset:8192
	ds_read_b128 v[152:155], v255 offset:10240
	ds_read_b128 v[136:139], v254 offset:12288
	ds_read_b128 v[128:131], v254 offset:14336
	ds_read_b128 v[140:143], v255 offset:12288
	ds_read_b128 v[132:135], v255 offset:14336
	v_max_f32_e32 v1, v160, v161
	v_max3_f32 v1, v1, v162, v163
	v_max3_f32 v1, v1, v164, v165
	v_max3_f32 v1, v1, v166, v167
	v_max3_f32 v1, v1, v168, v169
	v_max3_f32 v1, v1, v170, v171
	v_max3_f32 v1, v1, v172, v173
	v_max3_f32 v1, v1, v174, v175
	v_max3_f32 v1, v1, v112, v113
	v_max3_f32 v1, v1, v114, v115
	v_max3_f32 v1, v1, v116, v117
	v_max3_f32 v1, v1, v118, v119
	v_max3_f32 v1, v1, v120, v121
	v_max3_f32 v1, v1, v122, v123
	v_max3_f32 v1, v1, v124, v125
	v_max3_f32 v1, v1, v126, v127
	v_cmp_lt_f32_e32 vcc, s80, v1
	s_cbranch_vccnz .LBB0_384

; #define SBAR() __builtin_amdgcn_sched_barrier(0)
; #define QKT(P0, P1, b) qkt(P0, P1, nm, K_lds + (b) * SHM_T, qr, ko, c00, c01, c10, c11)
; #define PIPE1() do { SGB(0x100, 8); SGB(0x400, 4); SGB(0x008, 1); SGB(0x400, 4); SGB(0x008, 1); SGB(0x400, 4); SGB(0x008, 1); SGB(0x400, 4); SGB(0x008, 1); } while (0)
; __device__ __forceinline__ void finishSM(f32x16& p0, f32x16& p1, v8i& pf) {
;   for (int r = 0; r < 16; ++r) p1[r] = __builtin_amdgcn_exp2f(p1[r]);
; #pragma unroll
;   for (int j = 0; j < 4; ++j) {
;     int a = __builtin_amdgcn_cvt_pk_fp8_f32(p0[4 * j], p0[4 * j + 1], 0, false); a = __builtin_amdgcn_cvt_pk_fp8_f32(p0[4 * j + 2], p0[4 * j + 3], a, true);
;     int b = __builtin_amdgcn_cvt_pk_fp8_f32(p1[4 * j], p1[4 * j + 1], 0, false); b = __builtin_amdgcn_cvt_pk_fp8_f32(p1[4 * j + 2], p1[4 * j + 3], b, true);
;     auto rr = __builtin_amdgcn_permlane32_swap((unsigned)a, (unsigned)b, false, false);
;     pf[2 * j] = (int)rr[0]; pf[2 * j + 1] = (int)rr[1]; }
; }
; __device__ __forceinline__ void body(const unsigned char* Q8b, const unsigned char* K8h, const unsigned char* VT8h, const bf16_t* Gb, bf16_t* Ob, int seq, char* lds, const int wid, ...
;     ...
;     SBAR(); QKT(pB0, pB1, (s0 + 1) & 3);
;     finishSM(pA0, pA1, pf); PIPE1(); SBAR();
.Lc2_374:
	ds_read_b128 v[2:5], v242 offset:57344
	ds_read_b128 v[6:9], v243 offset:57344
	ds_read_b128 v[128:131], v242 offset:61440
	ds_read_b128 v[132:135], v243 offset:61440
	ds_read_b128 v[194:197], v244 offset:57344
	ds_read_b128 v[198:201], v245 offset:57344
	ds_read_b128 v[246:249], v244 offset:61440
	ds_read_b128 v[250:253], v245 offset:61440
	v_exp_f32_e32 v1, v112
	v_exp_f32_e32 v10, v113
	v_exp_f32_e32 v11, v114
	v_exp_f32_e32 v12, v115
	v_exp_f32_e32 v13, v120
	v_exp_f32_e32 v14, v121
	v_exp_f32_e32 v15, v122
	v_exp_f32_e32 v112, v123
	s_waitcnt lgkmcnt(6)
	s_setprio 1
	v_mfma_scale_f32_32x32x64_f8f6f4 v[160:175], v[2:9], v[176:183], v[96:111], v240, v239 op_sel_hi:[0,0,0]
	v_exp_f32_e32 v6, v116
	v_exp_f32_e32 v7, v117
	v_exp_f32_e32 v8, v118
	v_exp_f32_e32 v9, v119
	v_cvt_pk_fp8_f32 v5, v6, v7
	v_cvt_pk_fp8_f32 v3, v1, v10
	v_cvt_pk_fp8_f32 v5, v8, v9 op_sel:[0,0,1]
	s_waitcnt lgkmcnt(4)
	v_mfma_scale_f32_32x32x64_f8f6f4 v[128:143], v[128:135], v[176:183], v[96:111], v240, v239 op_sel_hi:[0,0,0]
	v_cvt_pk_fp8_f32 v2, v144, v145
	v_cvt_pk_fp8_f32 v4, v148, v149
	v_cvt_pk_fp8_f32 v6, v152, v153
	v_cvt_pk_fp8_f32 v7, v13, v14
	v_cvt_pk_fp8_f32 v8, v156, v157
	v_cvt_pk_fp8_f32 v2, v146, v147 op_sel:[0,0,1]
	v_cvt_pk_fp8_f32 v3, v11, v12 op_sel:[0,0,1]
	v_cvt_pk_fp8_f32 v4, v150, v151 op_sel:[0,0,1]
	v_cvt_pk_fp8_f32 v6, v154, v155 op_sel:[0,0,1]
	v_cvt_pk_fp8_f32 v7, v15, v112 op_sel:[0,0,1]
	v_cvt_pk_fp8_f32 v8, v158, v159 op_sel:[0,0,1]
	s_waitcnt lgkmcnt(2)
	v_mfma_scale_f32_32x32x64_f8f6f4 v[160:175], v[194:201], v[184:191], v[160:175], v240, v239 op_sel_hi:[0,0,0]
	v_exp_f32_e32 v113, v124
	v_exp_f32_e32 v114, v125
	v_exp_f32_e32 v1, v126
	v_exp_f32_e32 v10, v127
	v_permlane32_swap_b32_e32 v2, v3
	v_cvt_pk_fp8_f32 v9, v113, v114
	v_permlane32_swap_b32_e32 v4, v5
	v_permlane32_swap_b32_e32 v6, v7
	v_cvt_pk_fp8_f32 v9, v1, v10 op_sel:[0,0,1]
	s_nop 1
	v_permlane32_swap_b32_e32 v8, v9
	s_waitcnt lgkmcnt(0)
	v_mfma_scale_f32_32x32x64_f8f6f4 v[128:143], v[246:253], v[184:191], v[128:143], v240, v239 op_sel_hi:[0,0,0]
	s_setprio 0
	s_add_i32 m0, s68, 0xa000
	s_nop 0
	global_load_lds_dwordx4 v192, s[98:99]
	s_add_i32 m0, s68, 0x2000
	s_nop 0
	global_load_lds_dwordx4 v193, s[100:101]
	ds_read_b128 v[194:197], v254 offset:16384
	ds_read_b128 v[148:151], v254 offset:18432
	ds_read_b128 v[198:201], v255 offset:16384
	ds_read_b128 v[152:155], v255 offset:18432
	ds_read_b128 v[120:123], v254 offset:20480
	ds_read_b128 v[112:115], v254 offset:22528
	ds_read_b128 v[124:127], v255 offset:20480
	ds_read_b128 v[116:119], v255 offset:22528
	v_max_f32_e32 v1, v160, v161
	v_max3_f32 v1, v1, v162, v163
	v_max3_f32 v1, v1, v164, v165
	v_max3_f32 v1, v1, v166, v167
	v_max3_f32 v1, v1, v168, v169
	v_max3_f32 v1, v1, v170, v171
	v_max3_f32 v1, v1, v172, v173
	v_max3_f32 v1, v1, v174, v175
	v_max3_f32 v1, v1, v128, v129
	v_max3_f32 v1, v1, v130, v131
	v_max3_f32 v1, v1, v132, v133
	v_max3_f32 v1, v1, v134, v135
	v_max3_f32 v1, v1, v136, v137
	v_max3_f32 v1, v1, v138, v139
	v_max3_f32 v1, v1, v140, v141
	v_max3_f32 v1, v1, v142, v143
	v_cmp_lt_f32_e32 vcc, s80, v1
	s_cbranch_vccnz .Lc2_383

; #define SBAR() __builtin_amdgcn_sched_barrier(0)
; #define QKT(P0, P1, b) qkt(P0, P1, nm, K_lds + (b) * SHM_T, qr, ko, c00, c01, c10, c11)
; #define PIPE1() do { SGB(0x100, 8); SGB(0x400, 4); SGB(0x008, 1); SGB(0x400, 4); SGB(0x008, 1); SGB(0x400, 4); SGB(0x008, 1); SGB(0x400, 4); SGB(0x008, 1); } while (0)
; __device__ __forceinline__ void finishSM(f32x16& p0, f32x16& p1, v8i& pf) {
;   for (int r = 0; r < 16; ++r) p1[r] = __builtin_amdgcn_exp2f(p1[r]);
; #pragma unroll
;   for (int j = 0; j < 4; ++j) {
;     int a = __builtin_amdgcn_cvt_pk_fp8_f32(p0[4 * j], p0[4 * j + 1], 0, false); a = __builtin_amdgcn_cvt_pk_fp8_f32(p0[4 * j + 2], p0[4 * j + 3], a, true);
;     int b = __builtin_amdgcn_cvt_pk_fp8_f32(p1[4 * j], p1[4 * j + 1], 0, false); b = __builtin_amdgcn_cvt_pk_fp8_f32(p1[4 * j + 2], p1[4 * j + 3], b, true);
;     auto rr = __builtin_amdgcn_permlane32_swap((unsigned)a, (unsigned)b, false, false);
;     pf[2 * j] = (int)rr[0]; pf[2 * j + 1] = (int)rr[1]; }
; }
; __device__ __forceinline__ void body(const unsigned char* Q8b, const unsigned char* K8h, const unsigned char* VT8h, const bf16_t* Gb, bf16_t* Ob, int seq, char* lds, const int wid, ...
;     ...
;     SBAR(); QKT(pA0, pA1, (s0 + 2) & 3);
;     finishSM(pB0, pB1, pf); PIPE1(); SBAR();
.Lc2stg_a1:
	ds_read_b128 v[2:5], v242 offset:32768
	ds_read_b128 v[6:9], v243 offset:32768
	ds_read_b128 v[112:115], v242 offset:36864
	ds_read_b128 v[116:119], v243 offset:36864
	ds_read_b128 v[194:197], v244 offset:32768
	ds_read_b128 v[198:201], v245 offset:32768
	ds_read_b128 v[246:249], v244 offset:36864
	ds_read_b128 v[250:253], v245 offset:36864
	v_exp_f32_e32 v1, v128
	v_exp_f32_e32 v10, v129
	v_exp_f32_e32 v11, v130
	v_exp_f32_e32 v12, v131
	v_exp_f32_e32 v13, v136
	v_exp_f32_e32 v14, v137
	v_exp_f32_e32 v15, v138
	v_exp_f32_e32 v128, v139
	s_waitcnt lgkmcnt(6)
	s_setprio 1
	v_mfma_scale_f32_32x32x64_f8f6f4 v[160:175], v[2:9], v[176:183], v[96:111], v240, v239 op_sel_hi:[0,0,0]
	v_exp_f32_e32 v6, v132
	v_exp_f32_e32 v7, v133
	v_exp_f32_e32 v8, v134
	v_exp_f32_e32 v9, v135
	v_cvt_pk_fp8_f32 v5, v6, v7
	v_cvt_pk_fp8_f32 v2, v144, v145
	v_cvt_pk_fp8_f32 v5, v8, v9 op_sel:[0,0,1]
	s_waitcnt lgkmcnt(4)
	v_mfma_scale_f32_32x32x64_f8f6f4 v[112:127], v[112:119], v[176:183], v[96:111], v240, v239 op_sel_hi:[0,0,0]
	v_cvt_pk_fp8_f32 v3, v1, v10
	v_cvt_pk_fp8_f32 v4, v148, v149
	v_cvt_pk_fp8_f32 v6, v152, v153
	v_cvt_pk_fp8_f32 v7, v13, v14
	v_cvt_pk_fp8_f32 v8, v156, v157
	v_cvt_pk_fp8_f32 v2, v146, v147 op_sel:[0,0,1]
	v_cvt_pk_fp8_f32 v3, v11, v12 op_sel:[0,0,1]
	v_cvt_pk_fp8_f32 v4, v150, v151 op_sel:[0,0,1]
	v_cvt_pk_fp8_f32 v6, v154, v155 op_sel:[0,0,1]
	v_cvt_pk_fp8_f32 v7, v15, v128 op_sel:[0,0,1]
	v_cvt_pk_fp8_f32 v8, v158, v159 op_sel:[0,0,1]
	s_waitcnt lgkmcnt(2)
	v_mfma_scale_f32_32x32x64_f8f6f4 v[160:175], v[194:201], v[184:191], v[160:175], v240, v239 op_sel_hi:[0,0,0]
	v_exp_f32_e32 v129, v140
	v_exp_f32_e32 v130, v141
	v_exp_f32_e32 v131, v142
	v_exp_f32_e32 v132, v143
	v_permlane32_swap_b32_e32 v2, v3
	v_cvt_pk_fp8_f32 v9, v129, v130
	v_permlane32_swap_b32_e32 v4, v5
	v_permlane32_swap_b32_e32 v6, v7
	v_cvt_pk_fp8_f32 v9, v131, v132 op_sel:[0,0,1]
	s_nop 1
	v_permlane32_swap_b32_e32 v8, v9
	s_waitcnt lgkmcnt(0)
	v_mfma_scale_f32_32x32x64_f8f6f4 v[112:127], v[246:253], v[184:191], v[112:127], v240, v239 op_sel_hi:[0,0,0]
	s_setprio 0
	s_min_u32 s36, s45, 0x7b
	s_add_i32 s56, s36, 4
	s_lshl_b32 s36, s56, 14
	s_add_i32 s57, s68, 0x4000
	s_add_u32 s88, s94, s36
	s_addc_u32 s89, s95, 0
	s_add_i32 m0, s57, 0x8000
	s_lshl_b32 s36, s56, 13
	s_add_u32 s90, s96, s36
	s_addc_u32 s91, s97, 0
	global_load_lds_dwordx4 v192, s[88:89]
	s_mov_b32 m0, s57
	s_nop 0
	global_load_lds_dwordx4 v193, s[90:91]
	ds_read_b128 v[194:197], v254 offset:24576
	ds_read_b128 v[148:151], v254 offset:26624
	ds_read_b128 v[198:201], v255 offset:24576
	ds_read_b128 v[152:155], v255 offset:26624
	ds_read_b128 v[136:139], v254 offset:28672
	ds_read_b128 v[128:131], v254 offset:30720
	ds_read_b128 v[140:143], v255 offset:28672
	ds_read_b128 v[132:135], v255 offset:30720
	v_max_f32_e32 v1, v160, v161
	v_max3_f32 v1, v1, v162, v163
	v_max3_f32 v1, v1, v164, v165
	v_max3_f32 v1, v1, v166, v167
	v_max3_f32 v1, v1, v168, v169
	v_max3_f32 v1, v1, v170, v171
	v_max3_f32 v1, v1, v172, v173
	v_max3_f32 v1, v1, v174, v175
	v_max3_f32 v1, v1, v112, v113
	v_max3_f32 v1, v1, v114, v115
	v_max3_f32 v1, v1, v116, v117
	v_max3_f32 v1, v1, v118, v119
	v_max3_f32 v1, v1, v120, v121
	v_max3_f32 v1, v1, v122, v123
	v_max3_f32 v1, v1, v124, v125
	v_max3_f32 v1, v1, v126, v127
	v_cmp_lt_f32_e32 vcc, s80, v1
	s_cbranch_vccnz .Lc2_384
